# P7 and P15 row loops: loop-top vmcnt(0) replaced by counted waits (stores of the previous row stay in flight), first entry drained in front of the loop
# speedup vs baseline: 1.0111x; 1.0097x over previous
; __global__ void __launch_bounds__(512, 2) fwd_megakernel(Params p) {
;     ...
;             for (int tk = gw; tk < NB * 32 * 16; tk += NGW) {
;                 const int g = tk & 15, bn = tk >> 4;
;                 const bf16_t* vb = VT + ((size_t)bn * 16 + g) * 64 * 128;
;                 const bf16_t* wb = WSB + (size_t)g * 128 * 128;
;                 bf16x8 vf[4][4];
; #pragma unroll
;                 for (int nt = 0; nt < 4; ++nt)
; #pragma unroll
;                     for (int kk = 0; kk < 4; ++kk) vf[nt][kk] = *(const bf16x8*)(vb + (nt * 16 + fr) * 128 + kk * 32 + fq * 8);
;                 bf16x8 wfn[4]; u32x2 un[4]; float bsn;
;     ...
;                 P7_LOAD(0);
; #pragma unroll 2
;                 for (int mt = 0; mt < 8; ++mt) {
;                     bf16x8 wf[4]; u32x2 uc[4]; const float bsv = bsn;
; #pragma unroll
;                     for (int kk = 0; kk < 4; ++kk) { wf[kk] = wfn[kk]; uc[kk] = un[kk]; }
;                     { const int mtn = mt < 7 ? mt + 1 : 7; P7_LOAD(mtn); }
;                     f32x4 acc[4];
; #pragma unroll
;                     for (int nt = 0; nt < 4; ++nt) { acc[nt] = (f32x4){0.f, 0.f, 0.f, 0.f};
; #pragma unroll
;                         for (int kk = 0; kk < 4; ++kk) acc[nt] = __builtin_amdgcn_mfma_f32_16x16x32_bf16(vf[nt][kk], wf[kk], acc[nt], 0, 0, 0); }
.LBB0_632:
	s_ashr_i32 s46, s44, 4
	s_and_b32 s16, s31, 15
	s_ashr_i32 s47, s46, 31
	s_lshl_b32 s4, s16, 15
	s_lshl_b32 s27, s16, 7
	s_and_b32 s45, s44, 15
	s_lshl_b64 s[16:17], s[46:47], 18
	s_add_u32 s16, s22, s16
	s_addc_u32 s17, s23, s17
	s_lshl_b32 s20, s45, 14
	s_add_u32 s16, s16, s20
	s_addc_u32 s17, s17, 0
	s_lshl_b32 s20, s45, 15
	v_lshl_add_u64 v[0:1], s[16:17], 0, v[106:107]
	v_lshl_add_u64 v[44:45], v[0:1], 0, v[108:109]
	s_add_u32 s52, s24, s20
	v_add_co_u32_e32 v46, vcc, s35, v44
	s_addc_u32 s53, s25, 0
	s_lshl_b64 s[16:17], s[46:47], 7
	v_addc_co_u32_e32 v47, vcc, 0, v45, vcc
	s_waitcnt vmcnt(0)
	v_or_b32_e32 v78, s16, v96
	v_add_co_u32_e32 v40, vcc, s36, v44
	v_mad_u64_u32 v[78:79], s[20:21], v78, s33, v[110:111]
	s_nop 0
	v_addc_co_u32_e32 v41, vcc, 0, v45, vcc
	v_mad_i32_i24 v79, s17, v127, v79
	s_lshl_b32 s20, s45, 7
	s_mov_b32 s21, s5
	v_add_co_u32_e32 v60, vcc, s37, v44
	v_lshl_add_u64 v[78:79], v[78:79], 0, s[20:21]
	global_load_dwordx4 v[0:3], v[44:45], off
	global_load_dwordx4 v[4:7], v[44:45], off offset:64
	global_load_dwordx4 v[8:11], v[44:45], off offset:128
	global_load_dwordx4 v[12:15], v[44:45], off offset:192
	global_load_dwordx4 v[16:19], v[46:47], off offset:64
	global_load_dwordx4 v[20:23], v[46:47], off offset:128
	global_load_dwordx4 v[24:27], v[40:41], off offset:-4096
	global_load_dwordx4 v[28:31], v[40:41], off
	global_load_dwordx4 v[32:35], v[40:41], off offset:64
	global_load_dwordx4 v[36:39], v[40:41], off offset:128
	s_nop 0
	global_load_dwordx4 v[40:43], v[40:41], off offset:192
	v_addc_co_u32_e32 v61, vcc, 0, v45, vcc
	v_lshl_add_u64 v[62:63], s[52:53], 0, v[108:109]
	v_lshl_add_u64 v[78:79], v[78:79], 0, v[114:115]
	v_lshl_add_u64 v[76:77], v[62:63], 0, v[106:107]
	v_add_co_u32_e32 v82, vcc, s35, v78
	global_load_dwordx4 v[44:47], v[46:47], off offset:192
	s_nop 0
	global_load_dwordx4 v[48:51], v[60:61], off
	global_load_dwordx4 v[52:55], v[60:61], off offset:64
	global_load_dwordx4 v[56:59], v[60:61], off offset:128
	s_nop 0
	global_load_dwordx4 v[60:63], v[60:61], off offset:192
	s_nop 0
	global_load_dwordx4 v[72:75], v[76:77], off
	global_load_dwordx4 v[68:71], v[76:77], off offset:64
	global_load_dwordx4 v[64:67], v[76:77], off offset:128
	v_lshl_add_u64 v[80:81], v[78:79], 0, s[6:7]
	v_addc_co_u32_e32 v83, vcc, 0, v79, vcc
	global_load_dwordx4 v[76:79], v[76:77], off offset:192
	s_nop 0
	global_load_dwordx2 v[138:139], v[80:81], off offset:32
	global_load_dwordx2 v[142:143], v[82:83], off offset:2560
	global_load_dwordx2 v[134:135], v[80:81], off offset:64
	global_load_dwordx2 v[128:129], v[80:81], off offset:96
	v_or_b32_e32 v80, s20, v96
	v_lshlrev_b32_e32 v80, 2, v80
	global_load_dword v126, v80, s[18:19]
	v_or_b32_e32 v80, s27, v97
	v_lshl_add_u64 v[120:121], s[52:53], 0, v[106:107]
	s_lshl_b64 s[52:53], s[46:47], 19
	s_mul_i32 s21, s46, 0x150000
	v_lshl_add_u64 v[116:117], v[102:103], 0, s[4:5]
	v_lshlrev_b32_e32 v98, 2, v80
	s_lshl_b32 s4, s45, 6
	s_or_b32 s52, s52, s27
	s_mul_hi_i32 s47, s46, 0x150000
	s_or_b32 s46, s21, s27
	v_lshl_add_u64 v[118:119], s[18:19], 0, v[98:99]
	v_lshl_add_u64 v[122:123], s[52:53], 0, v[100:101]
	v_lshl_add_u64 v[124:125], s[46:47], 0, v[104:105]
	s_lshl_b32 s4, s4, 1
	s_mov_b32 s21, 32
	s_waitcnt vmcnt(0)
.LBB0_633:
	s_waitcnt vmcnt(4)
	v_cvt_f32_f16_e32 v158, v142
	v_cvt_f32_f16_sdwa v159, v142 dst_sel:DWORD dst_unused:UNUSED_PAD src0_sel:WORD_1
	v_mfma_f32_16x16x32_bf16 v[80:83], v[0:3], v[72:75], 0
	v_cvt_f32_f16_e32 v162, v143
	v_mul_f32_e32 v98, 0x3d372713, v158
	v_mul_f32_e32 v98, v98, v158
	v_mul_f32_e32 v113, 0x3d372713, v159
	v_fma_mix_f32 v98, v98, v142, v142 op_sel_hi:[0,1,1]
	v_mul_f32_e32 v113, v113, v159
	v_mul_f32_e32 v98, 0x3fcc422a, v98
	v_fma_mix_f32 v113, v113, v142, v142 op_sel:[0,1,1] op_sel_hi:[0,1,1]
	v_mul_f32_e32 v98, 0xbfb8aa3b, v98
	v_mul_f32_e32 v113, 0x3fcc422a, v113
	v_exp_f32_e32 v98, v98
	v_mul_f32_e32 v113, 0xbfb8aa3b, v113
	v_exp_f32_e32 v113, v113
	v_mfma_f32_16x16x32_bf16 v[130:133], v[4:7], v[68:71], v[80:83]
	v_cvt_f32_f16_sdwa v163, v143 dst_sel:DWORD dst_unused:UNUSED_PAD src0_sel:WORD_1
	v_add_f32_e32 v98, 1.0, v98
	v_lshl_add_u64 v[136:137], s[88:89], 0, v[116:117]
	v_lshl_add_u64 v[150:151], s[88:89], 0, v[124:125]
	v_rcp_f32_e32 v160, v98
	v_add_f32_e32 v98, 1.0, v113
	global_load_dwordx4 v[92:95], v[136:137], off offset:-128
	global_load_dwordx4 v[88:91], v[136:137], off offset:-64
	global_load_dwordx4 v[84:87], v[136:137], off
	global_load_dwordx4 v[80:83], v[136:137], off offset:64
	v_mfma_f32_16x16x32_bf16 v[146:149], v[8:11], v[64:67], v[130:133]
	global_load_dwordx2 v[144:145], v[150:151], off offset:-64
	global_load_dwordx2 v[140:141], v[150:151], off offset:-32
	global_load_dwordx2 v[136:137], v[150:151], off
	global_load_dwordx2 v[130:131], v[150:151], off offset:32
	v_rcp_f32_e32 v161, v98
	v_mul_f32_e32 v98, 0x3d372713, v162
	v_mfma_f32_16x16x32_bf16 v[150:153], v[24:27], v[72:75], 0
	v_mul_f32_e32 v113, 0x3d372713, v163
	v_mul_f32_e32 v98, v98, v162
	v_mul_f32_e32 v113, v113, v163
	v_mfma_f32_16x16x32_bf16 v[154:157], v[28:31], v[72:75], 0
	v_fma_mix_f32 v98, v98, v143, v143 op_sel_hi:[0,1,1]
	v_fma_mix_f32 v113, v113, v143, v143 op_sel:[0,1,1] op_sel_hi:[0,1,1]
	v_mul_f32_e32 v98, 0x3fcc422a, v98
	v_mfma_f32_16x16x32_bf16 v[72:75], v[48:51], v[72:75], 0
	v_mul_f32_e32 v113, 0x3fcc422a, v113
	v_mul_f32_e32 v98, 0xbfb8aa3b, v98
	v_exp_f32_e32 v98, v98
	v_mfma_f32_16x16x32_bf16 v[150:153], v[16:19], v[68:71], v[150:153]
	global_load_dword v132, v[118:119], off
	s_cmpk_lg_i32 s21, 0x80
	s_cselect_b32 s27, s21, 0x70
	v_mfma_f32_16x16x32_bf16 v[154:157], v[32:35], v[68:71], v[154:157]
; __device__ __forceinline__ unsigned cvt_pk_bf16(float lo, float hi) { const f32x2 v = (f32x2){lo, hi}; const bf16v2 b = __builtin_convertvector(v, bf16v2); return __builtin_bit_cast(unsigned, b); }
; __device__ __forceinline__ float gelu_t(float x) { return x * sigm(1.5957691216057308f * (x + 0.044715f * x * x * x)); }
; __global__ void __launch_bounds__(512, 2) fwd_megakernel(Params p) {
;     ...
;                     for (int nt = 0; nt < 4; ++nt) { acc[nt] = (f32x4){0.f, 0.f, 0.f, 0.f};
; #pragma unroll
;                         for (int kk = 0; kk < 4; ++kk) acc[nt] = __builtin_amdgcn_mfma_f32_16x16x32_bf16(vf[nt][kk], wf[kk], acc[nt], 0, 0, 0); }
;                     const int pt = mt * 16 + fr; const size_t m = (size_t)bn * 128 + pt;
; #pragma unroll
;                     for (int nt = 0; nt < 4; ++nt) {
;                         const int d0 = nt * 16 + fq * 4;
;                         const h16x4 uh = __builtin_bit_cast(h16x4, uc[nt]);
;                         float o[4];
; #pragma unroll
;                         for (int j = 0; j < 4; ++j) o[j] = gelu_t((float)uh[j]) * (acc[nt][j] + bsv);
;                         u32x2 w; w.x = cvt_pk_bf16(o[0], o[1]); w.y = cvt_pk_bf16(o[2], o[3]);
;                         *(u32x2*)(R0 + m * D + RW + g * 64 + d0) = w;
;                     }
	s_add_i32 s21, s21, 32
	v_lshl_add_u64 v[116:117], v[116:117], 0, s[10:11]
	v_lshl_add_u64 v[118:119], v[118:119], 0, s[12:13]
	v_mfma_f32_16x16x32_bf16 v[68:71], v[52:55], v[68:71], v[72:75]
	s_cmpk_eq_i32 s21, 0xa0
	v_lshl_add_u64 v[124:125], v[124:125], 0, s[14:15]
	s_nop 0
	v_mul_f32_e32 v72, 0xbfb8aa3b, v113
	v_exp_f32_e32 v72, v72
	v_mfma_f32_16x16x32_bf16 v[146:149], v[12:15], v[76:79], v[146:149]
	v_add_f32_e32 v73, 1.0, v98
	v_or_b32_e32 v98, s27, v96
	v_mov_b32_e32 v113, v99
	v_mfma_f32_16x16x32_bf16 v[150:153], v[20:23], v[64:67], v[150:153]
	v_mfma_f32_16x16x32_bf16 v[154:157], v[36:39], v[64:67], v[154:157]
	v_mfma_f32_16x16x32_bf16 v[64:67], v[56:59], v[64:67], v[68:71]
	s_nop 2
	v_add_f32_e32 v69, 1.0, v72
	v_rcp_f32_e32 v68, v73
	v_rcp_f32_e32 v69, v69
	v_pk_mul_f32 v[70:71], v[160:161], v[158:159]
	v_pk_add_f32 v[72:73], v[126:127], v[146:147] op_sel_hi:[0,1]
	v_pk_mul_f32 v[70:71], v[70:71], v[72:73]
	v_pk_mul_f32 v[68:69], v[68:69], v[162:163]
	v_pk_add_f32 v[72:73], v[126:127], v[148:149] op_sel_hi:[0,1]
	v_pk_mul_f32 v[68:69], v[68:69], v[72:73]
	v_cvt_f32_f16_e32 v72, v138
	v_cvt_f32_f16_sdwa v73, v138 dst_sel:DWORD dst_unused:UNUSED_PAD src0_sel:WORD_1
	v_lshl_add_u64 v[146:147], s[88:89], 0, v[122:123]
	v_cvt_pk_bf16_f32 v70, v70, v71
	v_cvt_pk_bf16_f32 v71, v68, v69
	v_add_co_u32_e32 v68, vcc, s42, v146
	v_mfma_f32_16x16x32_bf16 v[150:153], v[44:47], v[76:79], v[150:153]
	s_nop 0
	v_addc_co_u32_e32 v69, vcc, 0, v147, vcc
	global_store_dwordx2 v[68:69], v[70:71], off offset:2048
	v_mul_f32_e32 v70, 0x3d372713, v72
	v_mul_f32_e32 v71, 0x3d372713, v73
	v_mul_f32_e32 v70, v70, v72
	v_mul_f32_e32 v71, v71, v73
	v_fma_mix_f32 v70, v70, v138, v138 op_sel_hi:[0,1,1]
	v_fma_mix_f32 v71, v71, v138, v138 op_sel:[0,1,1] op_sel_hi:[0,1,1]
	v_mul_f32_e32 v70, 0x3fcc422a, v70
	v_mul_f32_e32 v71, 0x3fcc422a, v71
	v_mul_f32_e32 v70, 0xbfb8aa3b, v70
	v_mul_f32_e32 v71, 0xbfb8aa3b, v71
	v_exp_f32_e32 v70, v70
	v_exp_f32_e32 v71, v71
	v_mfma_f32_16x16x32_bf16 v[154:157], v[40:43], v[76:79], v[154:157]
	v_lshl_add_u64 v[122:123], v[122:123], 0, s[8:9]
	v_add_f32_e32 v74, 1.0, v70
	v_cvt_f32_f16_e32 v70, v139
	v_add_f32_e32 v75, 1.0, v71
	v_cvt_f32_f16_sdwa v71, v139 dst_sel:DWORD dst_unused:UNUSED_PAD src0_sel:WORD_1
	v_mfma_f32_16x16x32_bf16 v[64:67], v[60:63], v[76:79], v[64:67]
	v_mul_f32_e32 v76, 0x3d372713, v70
	v_mul_f32_e32 v76, v76, v70
	v_mul_f32_e32 v77, 0x3d372713, v71
	v_mul_f32_e32 v77, v77, v71
	v_fma_mix_f32 v76, v76, v139, v139 op_sel_hi:[0,1,1]
	v_fma_mix_f32 v77, v77, v139, v139 op_sel:[0,1,1] op_sel_hi:[0,1,1]
	v_mul_f32_e32 v76, 0x3fcc422a, v76
	v_mul_f32_e32 v77, 0x3fcc422a, v77
	v_mul_f32_e32 v76, 0xbfb8aa3b, v76
	v_mul_f32_e32 v77, 0xbfb8aa3b, v77
	v_exp_f32_e32 v76, v76
	v_exp_f32_e32 v77, v77
	v_rcp_f32_e32 v74, v74
	v_rcp_f32_e32 v75, v75
	v_add_f32_e32 v76, 1.0, v76
	v_add_f32_e32 v77, 1.0, v77
	v_rcp_f32_e32 v76, v76
	v_rcp_f32_e32 v77, v77
	v_pk_mul_f32 v[72:73], v[74:75], v[72:73]
	v_pk_add_f32 v[74:75], v[126:127], v[150:151] op_sel_hi:[0,1]
	v_pk_mul_f32 v[72:73], v[72:73], v[74:75]
	v_pk_mul_f32 v[70:71], v[76:77], v[70:71]
	v_pk_add_f32 v[74:75], v[126:127], v[152:153] op_sel_hi:[0,1]
	v_pk_mul_f32 v[70:71], v[70:71], v[74:75]
	v_cvt_f32_f16_e32 v74, v134
	v_cvt_f32_f16_sdwa v75, v134 dst_sel:DWORD dst_unused:UNUSED_PAD src0_sel:WORD_1
	v_cvt_pk_bf16_f32 v72, v72, v73
	v_cvt_pk_bf16_f32 v73, v70, v71
	v_mul_f32_e32 v70, 0x3d372713, v74
	v_mul_f32_e32 v71, 0x3d372713, v75
	v_mul_f32_e32 v70, v70, v74
	v_mul_f32_e32 v71, v71, v75
	v_fma_mix_f32 v70, v70, v134, v134 op_sel_hi:[0,1,1]
	v_fma_mix_f32 v71, v71, v134, v134 op_sel:[0,1,1] op_sel_hi:[0,1,1]
	v_mul_f32_e32 v70, 0x3fcc422a, v70
	v_mul_f32_e32 v71, 0x3fcc422a, v71
	v_mul_f32_e32 v70, 0xbfb8aa3b, v70
	v_mul_f32_e32 v71, 0xbfb8aa3b, v71
	v_exp_f32_e32 v70, v70
	v_exp_f32_e32 v71, v71
	global_store_dwordx2 v[68:69], v[72:73], off offset:2080
	v_cvt_f32_f16_e32 v78, v129
	v_add_f32_e32 v72, 1.0, v70
	v_cvt_f32_f16_e32 v70, v135
	v_add_f32_e32 v73, 1.0, v71
	v_cvt_f32_f16_sdwa v71, v135 dst_sel:DWORD dst_unused:UNUSED_PAD src0_sel:WORD_1
	v_rcp_f32_e32 v72, v72
	v_mul_f32_e32 v76, 0x3d372713, v70
	v_mul_f32_e32 v76, v76, v70
	v_mul_f32_e32 v77, 0x3d372713, v71
	v_mul_f32_e32 v77, v77, v71
	v_fma_mix_f32 v76, v76, v135, v135 op_sel_hi:[0,1,1]
	v_fma_mix_f32 v77, v77, v135, v135 op_sel:[0,1,1] op_sel_hi:[0,1,1]
	v_mul_f32_e32 v76, 0x3fcc422a, v76
	v_mul_f32_e32 v77, 0x3fcc422a, v77
	v_mul_f32_e32 v76, 0xbfb8aa3b, v76
	v_mul_f32_e32 v77, 0xbfb8aa3b, v77
	v_exp_f32_e32 v76, v76
	v_exp_f32_e32 v77, v77
	v_rcp_f32_e32 v73, v73
	v_cvt_f32_f16_sdwa v79, v129 dst_sel:DWORD dst_unused:UNUSED_PAD src0_sel:WORD_1
	v_add_f32_e32 v76, 1.0, v76
	v_add_f32_e32 v77, 1.0, v77
	v_rcp_f32_e32 v76, v76
	v_rcp_f32_e32 v77, v77
	v_pk_mul_f32 v[72:73], v[72:73], v[74:75]
	v_pk_add_f32 v[74:75], v[126:127], v[154:155] op_sel_hi:[0,1]
	v_pk_mul_f32 v[72:73], v[72:73], v[74:75]
	v_cvt_f32_f16_e32 v74, v128
	v_cvt_f32_f16_sdwa v75, v128 dst_sel:DWORD dst_unused:UNUSED_PAD src0_sel:WORD_1
	v_pk_mul_f32 v[70:71], v[76:77], v[70:71]
	v_pk_add_f32 v[76:77], v[126:127], v[156:157] op_sel_hi:[0,1]
	v_pk_mul_f32 v[70:71], v[70:71], v[76:77]
	v_mul_f32_e32 v76, 0x3d372713, v74
	v_mul_f32_e32 v76, v76, v74
	v_mul_f32_e32 v77, 0x3d372713, v75
	v_fma_mix_f32 v76, v76, v128, v128 op_sel_hi:[0,1,1]
	v_mul_f32_e32 v77, v77, v75
	v_mul_f32_e32 v76, 0x3fcc422a, v76
	v_fma_mix_f32 v77, v77, v128, v128 op_sel:[0,1,1] op_sel_hi:[0,1,1]
	v_mul_f32_e32 v76, 0xbfb8aa3b, v76
	v_mul_f32_e32 v77, 0x3fcc422a, v77
	v_exp_f32_e32 v76, v76
	v_mul_f32_e32 v77, 0xbfb8aa3b, v77
	v_exp_f32_e32 v77, v77
	v_cvt_pk_bf16_f32 v72, v72, v73
	v_add_f32_e32 v73, 1.0, v76
	v_rcp_f32_e32 v76, v73
	v_add_f32_e32 v73, 1.0, v77
	v_rcp_f32_e32 v77, v73
	v_cvt_pk_bf16_f32 v73, v70, v71
	v_mul_f32_e32 v70, 0x3d372713, v78
	v_mul_f32_e32 v70, v70, v78
	v_fma_mix_f32 v70, v70, v129, v129 op_sel_hi:[0,1,1]
	v_mul_f32_e32 v70, 0x3fcc422a, v70
	global_store_dwordx2 v[68:69], v[72:73], off offset:2112
	v_pk_mul_f32 v[74:75], v[76:77], v[74:75]
	v_mul_f32_e32 v76, 0xbfb8aa3b, v70
	s_waitcnt vmcnt(3)
; __device__ __forceinline__ unsigned cvt_pk_bf16(float lo, float hi) { const f32x2 v = (f32x2){lo, hi}; const bf16v2 b = __builtin_convertvector(v, bf16v2); return __builtin_bit_cast(unsigned, b); }
; __device__ __forceinline__ float gelu_t(float x) { return x * sigm(1.5957691216057308f * (x + 0.044715f * x * x * x)); }
; __global__ void __launch_bounds__(512, 2) fwd_megakernel(Params p) {
;     ...
;                 for (int mt = 0; mt < 8; ++mt) {
;                     bf16x8 wf[4]; u32x2 uc[4]; const float bsv = bsn;
; #pragma unroll
;                     for (int kk = 0; kk < 4; ++kk) { wf[kk] = wfn[kk]; uc[kk] = un[kk]; }
;                     { const int mtn = mt < 7 ? mt + 1 : 7; P7_LOAD(mtn); }
;                     f32x4 acc[4];
; #pragma unroll
;                     for (int nt = 0; nt < 4; ++nt) { acc[nt] = (f32x4){0.f, 0.f, 0.f, 0.f};
; #pragma unroll
;                         for (int kk = 0; kk < 4; ++kk) acc[nt] = __builtin_amdgcn_mfma_f32_16x16x32_bf16(vf[nt][kk], wf[kk], acc[nt], 0, 0, 0); }
;                     const int pt = mt * 16 + fr; const size_t m = (size_t)bn * 128 + pt;
; #pragma unroll
;                     for (int nt = 0; nt < 4; ++nt) {
;                         const int d0 = nt * 16 + fq * 4;
;                         const h16x4 uh = __builtin_bit_cast(h16x4, uc[nt]);
;                         float o[4];
; #pragma unroll
;                         for (int j = 0; j < 4; ++j) o[j] = gelu_t((float)uh[j]) * (acc[nt][j] + bsv);
;                         u32x2 w; w.x = cvt_pk_bf16(o[0], o[1]); w.y = cvt_pk_bf16(o[2], o[3]);
;                         *(u32x2*)(R0 + m * D + RW + g * 64 + d0) = w;
;                     }
	v_mfma_f32_16x16x32_bf16 v[70:73], v[0:3], v[92:95], 0
	v_mul_f32_e32 v77, 0x3d372713, v79
	v_mul_f32_e32 v77, v77, v79
	v_fma_mix_f32 v77, v77, v129, v129 op_sel:[0,1,1] op_sel_hi:[0,1,1]
	v_mfma_f32_16x16x32_bf16 v[70:73], v[4:7], v[88:91], v[70:73]
	v_mul_f32_e32 v77, 0x3fcc422a, v77
	v_mul_f32_e32 v77, 0xbfb8aa3b, v77
	v_exp_f32_e32 v76, v76
	v_mfma_f32_16x16x32_bf16 v[70:73], v[8:11], v[84:87], v[70:73]
	v_exp_f32_e32 v77, v77
	v_pk_add_f32 v[64:65], v[126:127], v[64:65] op_sel_hi:[0,1]
	v_add_f32_e32 v76, 1.0, v76
	v_mfma_f32_16x16x32_bf16 v[148:151], v[12:15], v[80:83], v[70:73]
	v_rcp_f32_e32 v76, v76
	v_pk_mul_f32 v[74:75], v[74:75], v[64:65]
	v_lshl_add_u64 v[128:129], s[16:17], 0, v[98:99]
	s_nop 0
	v_add_f32_e32 v70, 1.0, v77
	v_rcp_f32_e32 v77, v70
	v_mfma_f32_16x16x32_bf16 v[70:73], v[24:27], v[92:95], 0
	v_mov_b64_e32 v[134:135], s[2:3]
	v_mad_u64_u32 v[134:135], s[46:47], v128, s33, v[134:135]
	v_pk_mul_f32 v[76:77], v[76:77], v[78:79]
	v_pk_add_f32 v[78:79], v[126:127], v[66:67] op_sel_hi:[0,1]
	v_mfma_f32_16x16x32_bf16 v[64:67], v[16:19], v[88:91], v[70:73]
	v_mad_i32_i24 v135, v129, s33, v135
	v_lshl_add_u64 v[128:129], v[134:135], 0, s[4:5]
	v_lshl_add_u64 v[128:129], v[128:129], 0, v[112:113]
	v_mfma_f32_16x16x32_bf16 v[64:67], v[20:23], v[84:87], v[64:67]
	v_mul_f32_e64 v70, v76, v78
	v_mul_f32_e64 v71, v77, v79
	v_cvt_pk_bf16_f32 v72, v74, v75
	v_cvt_pk_bf16_f32 v73, v70, v71
	v_mfma_f32_16x16x32_bf16 v[152:155], v[44:47], v[80:83], v[64:67]
	global_store_dwordx2 v[68:69], v[72:73], off offset:2144
	v_lshlrev_b32_e32 v68, 8, v98
	v_mov_b32_e32 v69, v99
	v_mfma_f32_16x16x32_bf16 v[64:67], v[28:31], v[92:95], 0
	v_lshl_add_u64 v[160:161], v[128:129], 0, s[6:7]
	v_add_co_u32_e32 v128, vcc, s35, v128
	v_mfma_f32_16x16x32_bf16 v[92:95], v[48:51], v[92:95], 0
	v_add_u32_e32 v98, s20, v98
	v_lshl_add_u64 v[76:77], v[120:121], 0, v[68:69]
	v_addc_co_u32_e32 v129, vcc, 0, v129, vcc
	v_mfma_f32_16x16x32_bf16 v[156:159], v[32:35], v[88:91], v[64:67]
	global_load_dwordx4 v[72:75], v[76:77], off
	global_load_dwordx4 v[68:71], v[76:77], off offset:64
	s_nop 0
	global_load_dwordx4 v[64:67], v[76:77], off offset:128
	s_nop 0
	global_load_dwordx4 v[76:79], v[76:77], off offset:192
	s_nop 0
	global_load_dwordx2 v[142:143], v[128:129], off offset:2560
	global_load_dwordx2 v[138:139], v[160:161], off offset:32
	global_load_dwordx2 v[134:135], v[160:161], off offset:64
	s_nop 0
	global_load_dwordx2 v[128:129], v[160:161], off offset:96
	v_mfma_f32_16x16x32_bf16 v[88:91], v[52:55], v[88:91], v[92:95]
	v_mfma_f32_16x16x32_bf16 v[156:159], v[36:39], v[84:87], v[156:159]
	v_mfma_f32_16x16x32_bf16 v[84:87], v[56:59], v[84:87], v[88:91]
	s_nop 5
	v_cvt_f32_f16_e32 v90, v144
	v_cvt_f32_f16_sdwa v91, v144 dst_sel:DWORD dst_unused:UNUSED_PAD src0_sel:WORD_1
	v_mfma_f32_16x16x32_bf16 v[156:159], v[40:43], v[80:83], v[156:159]
	v_lshl_add_u64 v[88:89], v[98:99], 2, s[18:19]
	global_load_dword v126, v[88:89], off
	v_mfma_f32_16x16x32_bf16 v[80:83], v[60:63], v[80:83], v[84:87]
	s_nop 2
	v_mul_f32_e32 v84, 0x3d372713, v90
	v_mul_f32_e32 v85, 0x3d372713, v91
	v_mul_f32_e32 v84, v84, v90
	v_mul_f32_e32 v85, v85, v91
	v_fma_mix_f32 v84, v84, v144, v144 op_sel_hi:[0,1,1]
	v_fma_mix_f32 v85, v85, v144, v144 op_sel:[0,1,1] op_sel_hi:[0,1,1]
	v_mul_f32_e32 v84, 0x3fcc422a, v84
	v_mul_f32_e32 v85, 0x3fcc422a, v85
	v_mul_f32_e32 v84, 0xbfb8aa3b, v84
	v_mul_f32_e32 v85, 0xbfb8aa3b, v85
	v_exp_f32_e32 v84, v84
	v_exp_f32_e32 v85, v85
	v_pk_add_f32 v[80:81], v[132:133], v[80:81] op_sel_hi:[0,1]
	v_pk_add_f32 v[82:83], v[132:133], v[82:83] op_sel_hi:[0,1]
	v_add_f32_e32 v86, 1.0, v84
	v_cvt_f32_f16_e32 v84, v145
	v_add_f32_e32 v87, 1.0, v85
	v_cvt_f32_f16_sdwa v85, v145 dst_sel:DWORD dst_unused:UNUSED_PAD src0_sel:WORD_1
	v_rcp_f32_e32 v86, v86
	v_mul_f32_e32 v88, 0x3d372713, v84
	v_mul_f32_e32 v88, v88, v84
	v_mul_f32_e32 v89, 0x3d372713, v85
	v_mul_f32_e32 v89, v89, v85
	v_fma_mix_f32 v88, v88, v145, v145 op_sel_hi:[0,1,1]
	v_fma_mix_f32 v89, v89, v145, v145 op_sel:[0,1,1] op_sel_hi:[0,1,1]
	v_mul_f32_e32 v88, 0x3fcc422a, v88
	v_mul_f32_e32 v89, 0x3fcc422a, v89
	v_mul_f32_e32 v88, 0xbfb8aa3b, v88
	v_mul_f32_e32 v89, 0xbfb8aa3b, v89
	v_exp_f32_e32 v88, v88
	v_exp_f32_e32 v89, v89
	v_rcp_f32_e32 v87, v87
	v_add_f32_e32 v88, 1.0, v88
	v_add_f32_e32 v89, 1.0, v89
	v_rcp_f32_e32 v88, v88
	v_rcp_f32_e32 v89, v89
	v_pk_mul_f32 v[86:87], v[86:87], v[90:91]
	v_pk_add_f32 v[90:91], v[132:133], v[148:149] op_sel_hi:[0,1]
	v_pk_mul_f32 v[86:87], v[86:87], v[90:91]
	v_pk_mul_f32 v[84:85], v[88:89], v[84:85]
	v_pk_add_f32 v[88:89], v[132:133], v[150:151] op_sel_hi:[0,1]
	v_pk_mul_f32 v[84:85], v[84:85], v[88:89]
	v_cvt_pk_bf16_f32 v86, v86, v87
	v_cvt_pk_bf16_f32 v87, v84, v85
	v_cvt_f32_f16_e32 v84, v140
	v_cvt_f32_f16_sdwa v85, v140 dst_sel:DWORD dst_unused:UNUSED_PAD src0_sel:WORD_1
	v_add_co_u32_e32 v88, vcc, s43, v146
	s_nop 1
	v_addc_co_u32_e32 v89, vcc, 0, v147, vcc
	global_store_dwordx2 v[88:89], v[86:87], off offset:2048
	v_mul_f32_e32 v86, 0x3d372713, v84
	v_mul_f32_e32 v87, 0x3d372713, v85
; __device__ __forceinline__ unsigned cvt_pk_bf16(float lo, float hi) { const f32x2 v = (f32x2){lo, hi}; const bf16v2 b = __builtin_convertvector(v, bf16v2); return __builtin_bit_cast(unsigned, b); }
; __device__ __forceinline__ float gelu_t(float x) { return x * sigm(1.5957691216057308f * (x + 0.044715f * x * x * x)); }
; __global__ void __launch_bounds__(512, 2) fwd_megakernel(Params p) {
;     ...
;                     const int pt = mt * 16 + fr; const size_t m = (size_t)bn * 128 + pt;
; #pragma unroll
;                     for (int nt = 0; nt < 4; ++nt) {
;                         const int d0 = nt * 16 + fq * 4;
;                         const h16x4 uh = __builtin_bit_cast(h16x4, uc[nt]);
;                         float o[4];
; #pragma unroll
;                         for (int j = 0; j < 4; ++j) o[j] = gelu_t((float)uh[j]) * (acc[nt][j] + bsv);
;                         u32x2 w; w.x = cvt_pk_bf16(o[0], o[1]); w.y = cvt_pk_bf16(o[2], o[3]);
;                         *(u32x2*)(R0 + m * D + RW + g * 64 + d0) = w;
;                     }
;                 }
;     ...
;             }
	v_mul_f32_e32 v86, v86, v84
	v_mul_f32_e32 v87, v87, v85
	v_fma_mix_f32 v86, v86, v140, v140 op_sel_hi:[0,1,1]
	v_fma_mix_f32 v87, v87, v140, v140 op_sel:[0,1,1] op_sel_hi:[0,1,1]
	v_mul_f32_e32 v86, 0x3fcc422a, v86
	v_mul_f32_e32 v87, 0x3fcc422a, v87
	v_mul_f32_e32 v86, 0xbfb8aa3b, v86
	v_mul_f32_e32 v87, 0xbfb8aa3b, v87
	v_exp_f32_e32 v86, v86
	v_exp_f32_e32 v87, v87
	v_add_f32_e32 v90, 1.0, v86
	v_cvt_f32_f16_e32 v86, v141
	v_add_f32_e32 v91, 1.0, v87
	v_cvt_f32_f16_sdwa v87, v141 dst_sel:DWORD dst_unused:UNUSED_PAD src0_sel:WORD_1
	v_rcp_f32_e32 v90, v90
	v_mul_f32_e32 v92, 0x3d372713, v86
	v_mul_f32_e32 v92, v92, v86
	v_mul_f32_e32 v93, 0x3d372713, v87
	v_mul_f32_e32 v93, v93, v87
	v_fma_mix_f32 v92, v92, v141, v141 op_sel_hi:[0,1,1]
	v_fma_mix_f32 v93, v93, v141, v141 op_sel:[0,1,1] op_sel_hi:[0,1,1]
	v_mul_f32_e32 v92, 0x3fcc422a, v92
	v_mul_f32_e32 v93, 0x3fcc422a, v93
	v_mul_f32_e32 v92, 0xbfb8aa3b, v92
	v_mul_f32_e32 v93, 0xbfb8aa3b, v93
	v_exp_f32_e32 v92, v92
	v_exp_f32_e32 v93, v93
	v_rcp_f32_e32 v91, v91
	v_add_f32_e32 v92, 1.0, v92
	v_add_f32_e32 v93, 1.0, v93
	v_rcp_f32_e32 v92, v92
	v_rcp_f32_e32 v93, v93
	v_pk_mul_f32 v[84:85], v[90:91], v[84:85]
	v_pk_add_f32 v[90:91], v[132:133], v[152:153] op_sel_hi:[0,1]
	v_pk_mul_f32 v[84:85], v[84:85], v[90:91]
	v_pk_mul_f32 v[86:87], v[92:93], v[86:87]
	v_pk_add_f32 v[90:91], v[132:133], v[154:155] op_sel_hi:[0,1]
	v_pk_mul_f32 v[86:87], v[86:87], v[90:91]
	v_cvt_f32_f16_e32 v90, v136
	v_cvt_f32_f16_sdwa v91, v136 dst_sel:DWORD dst_unused:UNUSED_PAD src0_sel:WORD_1
	v_cvt_pk_bf16_f32 v84, v84, v85
	v_cvt_pk_bf16_f32 v85, v86, v87
	global_store_dwordx2 v[88:89], v[84:85], off offset:2080
	v_mul_f32_e32 v84, 0x3d372713, v90
	v_mul_f32_e32 v85, 0x3d372713, v91
	v_mul_f32_e32 v84, v84, v90
	v_mul_f32_e32 v85, v85, v91
	v_fma_mix_f32 v84, v84, v136, v136 op_sel_hi:[0,1,1]
	v_fma_mix_f32 v85, v85, v136, v136 op_sel:[0,1,1] op_sel_hi:[0,1,1]
	v_mul_f32_e32 v84, 0x3fcc422a, v84
	v_mul_f32_e32 v85, 0x3fcc422a, v85
	v_mul_f32_e32 v84, 0xbfb8aa3b, v84
	v_mul_f32_e32 v85, 0xbfb8aa3b, v85
	v_exp_f32_e32 v84, v84
	v_exp_f32_e32 v85, v85
	v_add_f32_e32 v86, 1.0, v84
	v_cvt_f32_f16_e32 v84, v137
	v_add_f32_e32 v87, 1.0, v85
	v_cvt_f32_f16_sdwa v85, v137 dst_sel:DWORD dst_unused:UNUSED_PAD src0_sel:WORD_1
	v_rcp_f32_e32 v86, v86
	v_mul_f32_e32 v92, 0x3d372713, v84
	v_mul_f32_e32 v92, v92, v84
	v_mul_f32_e32 v93, 0x3d372713, v85
	v_mul_f32_e32 v93, v93, v85
	v_fma_mix_f32 v92, v92, v137, v137 op_sel_hi:[0,1,1]
	v_fma_mix_f32 v93, v93, v137, v137 op_sel:[0,1,1] op_sel_hi:[0,1,1]
	v_mul_f32_e32 v92, 0x3fcc422a, v92
	v_mul_f32_e32 v93, 0x3fcc422a, v93
	v_mul_f32_e32 v92, 0xbfb8aa3b, v92
	v_mul_f32_e32 v93, 0xbfb8aa3b, v93
	v_exp_f32_e32 v92, v92
	v_exp_f32_e32 v93, v93
	v_rcp_f32_e32 v87, v87
	v_add_f32_e32 v92, 1.0, v92
	v_add_f32_e32 v93, 1.0, v93
	v_rcp_f32_e32 v92, v92
	v_rcp_f32_e32 v93, v93
	v_pk_mul_f32 v[86:87], v[86:87], v[90:91]
	v_pk_add_f32 v[90:91], v[132:133], v[156:157] op_sel_hi:[0,1]
	v_pk_mul_f32 v[86:87], v[86:87], v[90:91]
	v_pk_mul_f32 v[84:85], v[92:93], v[84:85]
	v_pk_add_f32 v[90:91], v[132:133], v[158:159] op_sel_hi:[0,1]
	v_pk_mul_f32 v[84:85], v[84:85], v[90:91]
	v_cvt_f32_f16_e32 v90, v130
	v_cvt_f32_f16_sdwa v91, v130 dst_sel:DWORD dst_unused:UNUSED_PAD src0_sel:WORD_1
	v_cvt_pk_bf16_f32 v86, v86, v87
	v_cvt_pk_bf16_f32 v87, v84, v85
	v_mul_f32_e32 v84, 0x3d372713, v90
	v_mul_f32_e32 v85, 0x3d372713, v91
	v_mul_f32_e32 v84, v84, v90
	v_mul_f32_e32 v85, v85, v91
	v_fma_mix_f32 v84, v84, v130, v130 op_sel_hi:[0,1,1]
	v_fma_mix_f32 v85, v85, v130, v130 op_sel:[0,1,1] op_sel_hi:[0,1,1]
	v_mul_f32_e32 v84, 0x3fcc422a, v84
	v_mul_f32_e32 v85, 0x3fcc422a, v85
	v_mul_f32_e32 v84, 0xbfb8aa3b, v84
	v_mul_f32_e32 v85, 0xbfb8aa3b, v85
	v_exp_f32_e32 v84, v84
	v_exp_f32_e32 v85, v85
	global_store_dwordx2 v[88:89], v[86:87], off offset:2112
	v_add_f32_e32 v86, 1.0, v84
	v_cvt_f32_f16_e32 v84, v131
	v_add_f32_e32 v87, 1.0, v85
	v_cvt_f32_f16_sdwa v85, v131 dst_sel:DWORD dst_unused:UNUSED_PAD src0_sel:WORD_1
	v_rcp_f32_e32 v86, v86
	v_mul_f32_e32 v92, 0x3d372713, v84
	v_mul_f32_e32 v92, v92, v84
	v_mul_f32_e32 v93, 0x3d372713, v85
	v_mul_f32_e32 v93, v93, v85
	v_fma_mix_f32 v92, v92, v131, v131 op_sel_hi:[0,1,1]
	v_fma_mix_f32 v93, v93, v131, v131 op_sel:[0,1,1] op_sel_hi:[0,1,1]
	v_mul_f32_e32 v92, 0x3fcc422a, v92
	v_mul_f32_e32 v93, 0x3fcc422a, v93
	v_mul_f32_e32 v92, 0xbfb8aa3b, v92
	v_mul_f32_e32 v93, 0xbfb8aa3b, v93
	v_exp_f32_e32 v92, v92
	v_exp_f32_e32 v93, v93
	v_rcp_f32_e32 v87, v87
	v_add_f32_e32 v92, 1.0, v92
	v_add_f32_e32 v93, 1.0, v93
	v_rcp_f32_e32 v92, v92
	v_rcp_f32_e32 v93, v93
	v_pk_mul_f32 v[86:87], v[86:87], v[90:91]
	v_pk_mul_f32 v[84:85], v[92:93], v[84:85]
	v_pk_mul_f32 v[80:81], v[86:87], v[80:81]
	v_pk_mul_f32 v[82:83], v[84:85], v[82:83]
	v_cvt_pk_bf16_f32 v80, v80, v81
	v_cvt_pk_bf16_f32 v81, v82, v83
	global_store_dwordx2 v[88:89], v[80:81], off offset:2144
	s_cbranch_scc0 .LBB0_633
	s_add_i32 s44, s44, s30
	s_sub_i32 s31, s31, s30
	s_cmpk_gt_i32 s44, 0xfff
	s_cbranch_scc0 .LBB0_632

; #define LAS __attribute__((address_space(3)))
; __global__ void __launch_bounds__(512, 2) fwd_megakernel(Params p) {
;     ...
;             const float* lg = lng + 2 * D; const float* lb = lnb + 2 * D;
;             LAS float* Lg = (LAS float*)lds; LAS float* Lb = Lg + D;
;             *(LAS f32x4*)(Lg + tid * 4) = *(const f32x4*)(lg + tid * 4); *(LAS f32x4*)(Lb + tid * 4) = *(const f32x4*)(lb + tid * 4);
;             __syncthreads();
;             f32x4 nv[8];
; #pragma unroll
;             for (int q = 0; q < 8; ++q) nv[q] = *(const f32x4*)(Yx + (size_t)gw * D + q * 256 + lane * 4);
;             for (int m = gw; m < MX; m += NGW) {
;                 float* yr = Yx + (size_t)m * D;
;                 f32x4 v[8]; float s = 0.f;
; #pragma unroll
;                 for (int q = 0; q < 8; ++q) { v[q] = nv[q]; s += (v[q][0] + v[q][1]) + (v[q][2] + v[q][3]); }
;                 { const int mn = m + NGW < MX ? m + NGW : m;
; #pragma unroll
;                   for (int q = 0; q < 8; ++q) nv[q] = *(const f32x4*)(Yx + (size_t)mn * D + q * 256 + lane * 4); }
;                 const float mean = wave_sum(s) * (1.0f / D); float s2 = 0.f;
.LBB0_1277:
	s_cmp_lt_i32 s90, 16
	s_cselect_b64 s[2:3], -1, 0
	s_and_b64 s[4:5], s[2:3], s[0:1]
	s_andn2_b64 vcc, exec, s[4:5]
	s_cbranch_vccnz .LBB0_1281
	v_mov_b32_e32 v181, 0
	v_lshl_add_u64 v[0:1], s[48:49], 0, v[180:181]
	v_add_co_u32_e32 v0, vcc, 0x4000, v0
	v_lshl_add_u64 v[4:5], s[50:51], 0, v[180:181]
	s_nop 0
	v_addc_co_u32_e32 v1, vcc, 0, v1, vcc
	v_add_co_u32_e32 v4, vcc, 0x4000, v4
	global_load_dwordx4 v[0:3], v[0:1], off
	s_nop 0
	v_addc_co_u32_e32 v5, vcc, 0, v5, vcc
	global_load_dwordx4 v[4:7], v[4:5], off
	v_add_u32_e32 v8, 0, v180
	s_cmpk_gt_i32 s34, 0x7fff
	s_waitcnt vmcnt(0)
	ds_write_b128 v8, v[0:3]
	ds_write_b128 v8, v[4:7] offset:8192
	s_waitcnt lgkmcnt(0)
	s_barrier
	s_cbranch_scc1 .LBB0_1281
	s_ashr_i32 s35, s34, 31
	s_lshl_b64 s[0:1], s[34:35], 13
	s_add_u32 s0, s86, s0
	v_lshlrev_b32_e32 v180, 4, v240
	s_addc_u32 s1, s87, s1
	v_lshl_add_u64 v[98:99], s[0:1], 0, v[180:181]
	v_add_co_u32_e32 v0, vcc, 0x1000, v98
	v_add_u32_e32 v84, 0, v180
	s_nop 0
	v_addc_co_u32_e32 v1, vcc, 0, v99, vcc
	global_load_dwordx4 v[20:23], v[0:1], off offset:3072
	global_load_dwordx4 v[36:39], v[0:1], off offset:2048
	global_load_dwordx4 v[52:55], v[0:1], off offset:1024
	global_load_dwordx4 v[80:83], v[0:1], off
	global_load_dwordx4 v[56:59], v180, s[0:1] offset:3072
	global_load_dwordx4 v[72:75], v180, s[0:1] offset:2048
	global_load_dwordx4 v[88:91], v180, s[0:1] offset:1024
	global_load_dwordx4 v[92:95], v180, s[0:1]
	v_mbcnt_lo_u32_b32 v0, -1, 0
	v_mbcnt_hi_u32_b32 v0, -1, v0
	v_and_b32_e32 v2, 64, v0
	v_xor_b32_e32 v1, 16, v0
	v_add_u32_e32 v2, 64, v2
	v_cmp_lt_i32_e32 vcc, v1, v2
	s_mov_b64 s[0:1], 0x1000
	s_ashr_i32 s31, s30, 31
	v_cndmask_b32_e32 v1, v0, v1, vcc
	v_lshlrev_b32_e32 v110, 2, v1
	v_xor_b32_e32 v1, 32, v0
	v_cmp_lt_i32_e32 vcc, v1, v2
	v_lshl_add_u64 v[96:97], s[86:87], 0, v[180:181]
	s_movk_i32 s8, 0x1000
	v_cndmask_b32_e32 v0, v0, v1, vcc
	v_lshlrev_b32_e32 v111, 2, v0
	ds_read_b128 v[0:3], v84
	ds_read_b128 v[4:7], v84 offset:1024
	ds_read_b128 v[8:11], v84 offset:8192
	ds_read_b128 v[12:15], v84 offset:9216
	ds_read_b128 v[16:19], v84 offset:2048
	ds_read_b128 v[24:27], v84 offset:3072
	ds_read_b128 v[28:31], v84 offset:10240
	ds_read_b128 v[32:35], v84 offset:11264
	ds_read_b128 v[40:43], v84 offset:4096
	ds_read_b128 v[44:47], v84 offset:5120
	ds_read_b128 v[48:51], v84 offset:12288
	ds_read_b128 v[60:63], v84 offset:13312
	ds_read_b128 v[64:67], v84 offset:6144
	ds_read_b128 v[68:71], v84 offset:7168
	ds_read_b128 v[76:79], v84 offset:14336
	ds_read_b128 v[84:87], v84 offset:15360
	v_lshl_add_u64 v[98:99], v[98:99], 0, s[0:1]
	s_lshl_b64 s[6:7], s[30:31], 13
	v_mov_b32_e32 v112, 0x3727c5ac
	s_mov_b32 s9, 0xf800000
	v_mov_b32_e32 v113, 0x260
	s_waitcnt vmcnt(0)
.LBB0_1280:
	s_add_i32 s1, s34, s30
	s_cmp_lt_i32 s1, 0x8000
	s_waitcnt vmcnt(8)
	v_mov_b32_e32 v102, v92
	v_mov_b32_e32 v103, v88
	v_mov_b32_e32 v104, v93
	v_mov_b32_e32 v105, v89
	v_mov_b32_e32 v106, v94
	v_mov_b32_e32 v107, v90
	v_mov_b32_e32 v108, v95
	v_mov_b32_e32 v109, v91
	s_cselect_b64 s[2:3], -1, 0
	v_mov_b32_e32 v114, v73
	v_mov_b32_e32 v115, v74
	v_mov_b32_e32 v116, v72
	v_mov_b32_e32 v117, v75
	v_add_f32_e32 v118, v56, v57
	v_add_f32_e32 v120, v58, v59
	v_mov_b32_e32 v119, v82
	v_mov_b32_e32 v121, v83
	v_pk_add_f32 v[104:105], v[102:103], v[104:105]
	v_pk_add_f32 v[108:109], v[106:107], v[108:109]
	s_and_b64 s[2:3], s[2:3], exec
	v_pk_add_f32 v[114:115], v[114:115], v[116:117]
	v_pk_add_f32 v[106:107], v[118:119], v[120:121]
	v_pk_add_f32 v[118:119], v[104:105], v[108:109]
	s_cselect_b32 s0, s1, s34
	v_pk_add_f32 v[108:109], v[114:115], v[114:115] op_sel:[0,1] op_sel_hi:[1,0]
	v_add_f32_e32 v100, 0, v118
	s_mov_b32 s34, s1
	s_ashr_i32 s1, s0, 31
	v_mov_b32_e32 v101, v80
	v_add_f32_e32 v126, v36, v37
	v_add_f32_e32 v128, v38, v39
	v_mov_b32_e32 v127, v22
	v_mov_b32_e32 v129, v23
	v_mov_b32_e32 v109, v81
	v_add_f32_e32 v100, v100, v119
	s_lshl_b64 s[0:1], s[0:1], 13
	v_mov_b32_e32 v122, v53
	v_mov_b32_e32 v123, v54
	v_mov_b32_e32 v124, v52
	v_mov_b32_e32 v125, v55
	v_pk_add_f32 v[102:103], v[126:127], v[128:129]
	v_pk_add_f32 v[100:101], v[100:101], v[108:109]
	v_lshl_add_u64 v[126:127], v[96:97], 0, s[0:1]
	v_pk_add_f32 v[116:117], v[122:123], v[124:125]
	v_pk_add_f32 v[100:101], v[100:101], v[106:107]
	v_add_co_u32_e32 v138, vcc, s8, v126
	v_pk_add_f32 v[104:105], v[116:117], v[116:117] op_sel:[0,1] op_sel_hi:[1,0]
	v_pk_add_f32 v[100:101], v[100:101], v[100:101] op_sel:[0,1] op_sel_hi:[1,0]
	v_addc_co_u32_e32 v139, vcc, 0, v127, vcc
	v_mov_b32_e32 v105, v21
	v_mov_b32_e32 v101, v20
	global_load_dwordx4 v[106:109], v[126:127], off
	global_load_dwordx4 v[114:117], v[126:127], off offset:1024
	global_load_dwordx4 v[118:121], v[126:127], off offset:2048
	global_load_dwordx4 v[122:125], v[126:127], off offset:3072
	s_nop 0
	global_load_dwordx4 v[126:129], v[138:139], off
	global_load_dwordx4 v[130:133], v[138:139], off offset:1024
	global_load_dwordx4 v[134:137], v[138:139], off offset:2048
	s_nop 0
	global_load_dwordx4 v[138:141], v[138:139], off offset:3072
	v_pk_add_f32 v[100:101], v[100:101], v[104:105]
	s_nop 0
	v_pk_add_f32 v[100:101], v[100:101], v[102:103]
	s_nop 0
	v_add_f32_e32 v100, v100, v101
	s_nop 1
	v_add_f32_dpp v100, v100, v100 quad_perm:[1,0,3,2] row_mask:0xf bank_mask:0xf bound_ctrl:1
	s_nop 1
	v_add_f32_dpp v100, v100, v100 quad_perm:[2,3,0,1] row_mask:0xf bank_mask:0xf bound_ctrl:1
	s_nop 1
	v_add_f32_dpp v100, v100, v100 row_half_mirror row_mask:0xf bank_mask:0xf bound_ctrl:1
	s_nop 1
	v_add_f32_dpp v100, v100, v100 row_mirror row_mask:0xf bank_mask:0xf bound_ctrl:1
	ds_bpermute_b32 v101, v110, v100
	s_waitcnt lgkmcnt(0)
; __global__ void __launch_bounds__(512, 2) fwd_megakernel(Params p) {
;     ...
;                 const float mean = wave_sum(s) * (1.0f / D); float s2 = 0.f;
; #pragma unroll
;                 for (int q = 0; q < 8; ++q) { v[q] = v[q] - mean; s2 += (v[q][0] * v[q][0] + v[q][1] * v[q][1]) + (v[q][2] * v[q][2] + v[q][3] * v[q][3]); }
;                 const float rstd = 1.0f / sqrtf(wave_sum(s2) * (1.0f / D) + LN_EPS);
	v_add_f32_e32 v100, v100, v101
	ds_bpermute_b32 v101, v111, v100
	s_waitcnt lgkmcnt(0)
	v_add_f32_e32 v100, v100, v101
	v_fmamk_f32 v95, v100, 0xba000000, v95
	v_fmamk_f32 v93, v100, 0xba000000, v93
	v_fmamk_f32 v91, v100, 0xba000000, v91
	v_fmamk_f32 v89, v100, 0xba000000, v89
	v_fmamk_f32 v94, v100, 0xba000000, v94
	v_fmac_f32_e32 v92, 0xba000000, v100
	v_fmamk_f32 v90, v100, 0xba000000, v90
	v_fmac_f32_e32 v88, 0xba000000, v100
	v_fmamk_f32 v73, v100, 0xba000000, v73
	v_fmamk_f32 v72, v100, 0xba000000, v72
	v_fmamk_f32 v75, v100, 0xba000000, v75
	v_fmac_f32_e32 v74, 0xba000000, v100
	v_mov_b32_e32 v102, v93
	v_mov_b32_e32 v103, v89
	v_mov_b32_e32 v142, v95
	v_mov_b32_e32 v143, v91
	v_fmamk_f32 v57, v100, 0xba000000, v57
	v_fmamk_f32 v56, v100, 0xba000000, v56
	v_fmamk_f32 v59, v100, 0xba000000, v59
	v_fmac_f32_e32 v58, 0xba000000, v100
	v_fmamk_f32 v83, v100, 0xba000000, v83
	v_fmamk_f32 v82, v100, 0xba000000, v82
	v_fmamk_f32 v81, v100, 0xba000000, v81
	v_fmac_f32_e32 v80, 0xba000000, v100
	v_fmamk_f32 v53, v100, 0xba000000, v53
	v_fmamk_f32 v52, v100, 0xba000000, v52
	v_fmamk_f32 v55, v100, 0xba000000, v55
	v_fmac_f32_e32 v54, 0xba000000, v100
	v_fmamk_f32 v37, v100, 0xba000000, v37
	v_fmamk_f32 v36, v100, 0xba000000, v36
	v_fmamk_f32 v39, v100, 0xba000000, v39
	v_fmac_f32_e32 v38, 0xba000000, v100
	v_fmamk_f32 v23, v100, 0xba000000, v23
	v_fmamk_f32 v22, v100, 0xba000000, v22
	v_fmamk_f32 v21, v100, 0xba000000, v21
	v_fmac_f32_e32 v20, 0xba000000, v100
	v_mov_b32_e32 v100, v92
	v_mov_b32_e32 v101, v88
	v_mov_b32_e32 v104, v94
	v_mov_b32_e32 v105, v90
	v_pk_mul_f32 v[144:145], v[74:75], v[74:75]
	v_pk_mul_f32 v[146:147], v[72:73], v[72:73]
	v_pk_mul_f32 v[102:103], v[102:103], v[102:103]
	v_pk_mul_f32 v[142:143], v[142:143], v[142:143]
	v_pk_mov_b32 v[160:161], v[146:147], v[144:145] op_sel:[1,0]
	v_mov_b32_e32 v147, v145
	v_pk_fma_f32 v[100:101], v[100:101], v[100:101], v[102:103]
	v_pk_fma_f32 v[102:103], v[104:105], v[104:105], v[142:143]
	v_mul_f32_e32 v148, v57, v57
	v_mul_f32_e32 v150, v59, v59
	v_pk_add_f32 v[104:105], v[160:161], v[146:147]
	v_pk_add_f32 v[100:101], v[100:101], v[102:103]
	v_mul_f32_e32 v159, v80, v80
	v_mul_f32_e32 v162, v81, v81
	v_mul_f32_e32 v163, v82, v82
	v_mul_f32_e32 v164, v83, v83
	v_pk_fma_f32 v[144:145], v[56:57], v[56:57], v[148:149] op_sel_hi:[1,1,0]
	v_pk_fma_f32 v[148:149], v[58:59], v[58:59], v[150:151] op_sel_hi:[1,1,0]
	v_pk_add_f32 v[102:103], v[104:105], v[104:105] op_sel:[0,1] op_sel_hi:[1,0]
	v_pk_add_f32 v[100:101], v[100:101], v[100:101] op_sel:[0,1] op_sel_hi:[1,0]
	v_pk_mul_f32 v[152:153], v[54:55], v[54:55]
	v_pk_mul_f32 v[154:155], v[52:53], v[52:53]
	v_mov_b32_e32 v145, v163
	v_mov_b32_e32 v149, v164
	v_mov_b32_e32 v103, v162
	v_mov_b32_e32 v101, v159
	v_pk_mov_b32 v[150:151], v[154:155], v[152:153] op_sel:[1,0]
	v_mov_b32_e32 v155, v153
	v_pk_add_f32 v[104:105], v[144:145], v[148:149]
	v_pk_add_f32 v[100:101], v[100:101], v[102:103]
	v_mul_f32_e32 v156, v37, v37
	v_mul_f32_e32 v158, v39, v39
	v_pk_add_f32 v[142:143], v[150:151], v[154:155]
	v_pk_add_f32 v[100:101], v[100:101], v[104:105]
	v_mul_f32_e32 v165, v20, v20
	v_mul_f32_e32 v166, v21, v21
	v_mul_f32_e32 v167, v22, v22
	v_mul_f32_e32 v168, v23, v23
	v_pk_fma_f32 v[152:153], v[36:37], v[36:37], v[156:157] op_sel_hi:[1,1,0]
	v_pk_fma_f32 v[156:157], v[38:39], v[38:39], v[158:159] op_sel_hi:[1,1,0]
	v_pk_add_f32 v[142:143], v[142:143], v[142:143] op_sel:[0,1] op_sel_hi:[1,0]
	v_pk_add_f32 v[100:101], v[100:101], v[100:101] op_sel:[0,1] op_sel_hi:[1,0]
	v_mov_b32_e32 v153, v167
	v_mov_b32_e32 v157, v168
	v_mov_b32_e32 v143, v166
	v_mov_b32_e32 v101, v165
	v_pk_add_f32 v[144:145], v[152:153], v[156:157]
	v_pk_add_f32 v[100:101], v[100:101], v[142:143]
	s_nop 0
	v_pk_add_f32 v[100:101], v[100:101], v[144:145]
	s_nop 0
	v_add_f32_e32 v100, v100, v101
	s_nop 1
	v_add_f32_dpp v100, v100, v100 quad_perm:[1,0,3,2] row_mask:0xf bank_mask:0xf bound_ctrl:1
	s_nop 1
	v_add_f32_dpp v100, v100, v100 quad_perm:[2,3,0,1] row_mask:0xf bank_mask:0xf bound_ctrl:1
	s_nop 1
	v_add_f32_dpp v100, v100, v100 row_half_mirror row_mask:0xf bank_mask:0xf bound_ctrl:1
	s_nop 1
	v_add_f32_dpp v100, v100, v100 row_mirror row_mask:0xf bank_mask:0xf bound_ctrl:1
	ds_bpermute_b32 v101, v110, v100
	s_waitcnt lgkmcnt(0)
; #define LAS __attribute__((address_space(3)))
; __global__ void __launch_bounds__(512, 2) fwd_megakernel(Params p) {
;     ...
;                 const float rstd = 1.0f / sqrtf(wave_sum(s2) * (1.0f / D) + LN_EPS);
;                 f32x4 g8[8], b8[8];
; #pragma unroll
;                 for (int q = 0; q < 8; ++q) { const int c = q * 256 + lane * 4; g8[q] = *(const LAS f32x4*)(Lg + c); b8[q] = *(const LAS f32x4*)(Lb + c); }
; #pragma unroll
;                 for (int q = 0; q < 8; ++q) { const int c = q * 256 + lane * 4; *(f32x4*)(yr + c) = v[q] * rstd * g8[q] + b8[q]; }
;             }
	v_add_f32_e32 v100, v100, v101
	ds_bpermute_b32 v101, v111, v100
	s_waitcnt lgkmcnt(0)
	v_add_f32_e32 v100, v100, v101
	v_fmamk_f32 v100, v100, 0x3a000000, v112
	v_mul_f32_e32 v101, 0x4f800000, v100
	v_cmp_gt_f32_e32 vcc, s9, v100
	s_nop 1
	v_cndmask_b32_e32 v100, v100, v101, vcc
	v_sqrt_f32_e32 v101, v100
	s_nop 0
	v_add_u32_e32 v102, -1, v101
	v_add_u32_e32 v103, 1, v101
	v_fma_f32 v104, -v102, v101, v100
	v_fma_f32 v105, -v103, v101, v100
	v_cmp_ge_f32_e64 s[0:1], 0, v104
	s_nop 1
	v_cndmask_b32_e64 v101, v101, v102, s[0:1]
	v_cmp_lt_f32_e64 s[0:1], 0, v105
	s_nop 1
	v_cndmask_b32_e64 v101, v101, v103, s[0:1]
	v_mul_f32_e32 v102, 0x37800000, v101
	v_cndmask_b32_e32 v101, v101, v102, vcc
	v_cmp_class_f32_e32 vcc, v100, v113
	s_nop 1
	v_cndmask_b32_e32 v100, v101, v100, vcc
	v_div_scale_f32 v101, s[0:1], v100, v100, 1.0
	v_rcp_f32_e32 v103, v101
	v_div_scale_f32 v102, vcc, 1.0, v100, 1.0
	v_fma_f32 v104, -v101, v103, 1.0
	v_fmac_f32_e32 v103, v104, v103
	v_mul_f32_e32 v104, v102, v103
	v_fma_f32 v105, -v101, v104, v102
	v_fmac_f32_e32 v104, v105, v103
	v_fma_f32 v101, -v101, v104, v102
	v_div_fmas_f32 v101, v101, v103, v104
	v_div_fixup_f32 v100, v101, v100, 1.0
	v_pk_mul_f32 v[92:93], v[100:101], v[92:93] op_sel_hi:[0,1]
	v_pk_mul_f32 v[94:95], v[100:101], v[94:95] op_sel_hi:[0,1]
	v_pk_mul_f32 v[88:89], v[100:101], v[88:89] op_sel_hi:[0,1]
	v_pk_mul_f32 v[90:91], v[100:101], v[90:91] op_sel_hi:[0,1]
	v_pk_mul_f32 v[72:73], v[100:101], v[72:73] op_sel_hi:[0,1]
	v_pk_mul_f32 v[74:75], v[100:101], v[74:75] op_sel_hi:[0,1]
	v_pk_mul_f32 v[56:57], v[100:101], v[56:57] op_sel_hi:[0,1]
	v_pk_mul_f32 v[58:59], v[100:101], v[58:59] op_sel_hi:[0,1]
	v_pk_mul_f32 v[80:81], v[100:101], v[80:81] op_sel_hi:[0,1]
	v_pk_mul_f32 v[82:83], v[100:101], v[82:83] op_sel_hi:[0,1]
	v_pk_mul_f32 v[102:103], v[100:101], v[52:53] op_sel_hi:[0,1]
	v_pk_mul_f32 v[104:105], v[100:101], v[54:55] op_sel_hi:[0,1]
	v_pk_mul_f32 v[142:143], v[100:101], v[36:37] op_sel_hi:[0,1]
	v_pk_mul_f32 v[144:145], v[100:101], v[38:39] op_sel_hi:[0,1]
	v_pk_mul_f32 v[146:147], v[100:101], v[20:21] op_sel_hi:[0,1]
	v_pk_mul_f32 v[100:101], v[100:101], v[22:23] op_sel_hi:[0,1]
	v_pk_fma_f32 v[22:23], v[94:95], v[2:3], v[10:11]
	v_pk_fma_f32 v[20:21], v[92:93], v[0:1], v[8:9]
	v_pk_fma_f32 v[38:39], v[90:91], v[6:7], v[14:15]
	v_pk_fma_f32 v[36:37], v[88:89], v[4:5], v[12:13]
	v_pk_fma_f32 v[54:55], v[74:75], v[18:19], v[30:31]
	v_pk_fma_f32 v[52:53], v[72:73], v[16:17], v[28:29]
	v_pk_fma_f32 v[58:59], v[58:59], v[26:27], v[34:35]
	v_pk_fma_f32 v[56:57], v[56:57], v[24:25], v[32:33]
	v_pk_fma_f32 v[74:75], v[82:83], v[42:43], v[50:51]
	v_pk_fma_f32 v[72:73], v[80:81], v[40:41], v[48:49]
	v_pk_fma_f32 v[82:83], v[104:105], v[46:47], v[62:63]
	v_pk_fma_f32 v[80:81], v[102:103], v[44:45], v[60:61]
	v_pk_fma_f32 v[90:91], v[144:145], v[66:67], v[78:79]
	v_pk_fma_f32 v[88:89], v[142:143], v[64:65], v[76:77]
	v_pk_fma_f32 v[94:95], v[100:101], v[70:71], v[86:87]
	v_pk_fma_f32 v[92:93], v[146:147], v[68:69], v[84:85]
	global_store_dwordx4 v[98:99], v[20:23], off offset:-4096
	global_store_dwordx4 v[98:99], v[36:39], off offset:-3072
	global_store_dwordx4 v[98:99], v[52:55], off offset:-2048
	global_store_dwordx4 v[98:99], v[56:59], off offset:-1024
	global_store_dwordx4 v[98:99], v[72:75], off
	global_store_dwordx4 v[98:99], v[80:83], off offset:1024
	global_store_dwordx4 v[98:99], v[88:91], off offset:2048
	global_store_dwordx4 v[98:99], v[92:95], off offset:3072
	s_waitcnt vmcnt(12)
	v_mov_b64_e32 v[56:57], v[122:123]
	v_mov_b64_e32 v[72:73], v[118:119]
	v_mov_b64_e32 v[88:89], v[114:115]
	v_mov_b64_e32 v[92:93], v[106:107]
	s_waitcnt vmcnt(8)
	v_mov_b64_e32 v[20:21], v[138:139]
	v_mov_b64_e32 v[36:37], v[134:135]
	v_mov_b64_e32 v[52:53], v[130:131]
	v_mov_b64_e32 v[80:81], v[126:127]
	v_lshl_add_u64 v[98:99], v[98:99], 0, s[6:7]
	v_mov_b64_e32 v[58:59], v[124:125]
	v_mov_b64_e32 v[74:75], v[120:121]
	v_mov_b64_e32 v[90:91], v[116:117]
	v_mov_b64_e32 v[94:95], v[108:109]
	v_mov_b64_e32 v[22:23], v[140:141]
	v_mov_b64_e32 v[38:39], v[136:137]
	v_mov_b64_e32 v[54:55], v[132:133]
	v_mov_b64_e32 v[82:83], v[128:129]
	s_mov_b64 vcc, s[2:3]
	s_cbranch_vccnz .LBB0_1280
